# S5 full pass: LDS stores of projected inputs and states issued as ds_write2_b32 pairs (fewer LDS instructions); sample-GEMM start wait removed
# speedup vs baseline: 1.0232x; 1.0048x over previous
.LBB0_491:
	s_cmpk_gt_u32 s2, 0xff
	s_cbranch_scc1 .LBB0_496
	v_bfe_u32 v9, v129, 4, 2
	v_and_b32_e32 v0, 0xf00, v147
	v_mov_b32_e32 v1, 0
	v_lshl_add_u64 v[2:3], s[44:45], 0, v[0:1]
	v_lshlrev_b32_e32 v4, 4, v9
	v_mov_b32_e32 v5, v1
	v_lshl_add_u64 v[6:7], s[62:63], 0, v[0:1]
	v_lshl_add_u64 v[2:3], v[2:3], 0, v[4:5]
	v_lshl_add_u64 v[4:5], v[6:7], 0, v[4:5]
	v_lshlrev_b32_e32 v6, 7, v129
	v_lshrrev_b32_e32 v8, 4, v129
	v_and_b32_e32 v0, 7, v129
	v_and_b32_e32 v6, 0x1e780, v6
	v_add_u32_e32 v11, 0, v6
	v_bitop3_b32 v6, v8, v0, 3 bitop3:0x6c
	v_bitop3_b32 v0, v9, v0, 4 bitop3:0x36
	v_lshrrev_b32_e32 v8, 3, v129
	v_lshlrev_b32_e32 v12, 4, v0
	v_xor_b32_e32 v0, v8, v129
	v_lshlrev_b32_e32 v0, 4, v0
	v_lshlrev_b32_e32 v10, 4, v6
	v_lshlrev_b32_e32 v6, 7, v8
	v_and_b32_e32 v0, 0x70, v0
	v_add3_u32 v9, 0, v6, v0
	v_and_b32_e32 v0, 28, v147
	s_movk_i32 s4, 0x200
	v_lshlrev_b32_e32 v0, 1, v0
	v_cmp_gt_u32_e64 s[4:5], s4, v129
	v_lshl_add_u64 v[6:7], s[46:47], 0, v[0:1]
	s_lshl_b32 s10, s2, 2
	s_waitcnt lgkmcnt(0)
	s_lshl_b32 s11, s3, 2
	s_lshl_b32 s12, s2, 6
	s_lshl_b32 s13, s3, 6
	v_add_u32_e32 v10, v11, v10
	v_add_u32_e32 v11, v11, v12
	s_mov_b32 s14, s2
	s_branch .LBB0_494

.LBB0_707:
	s_cmpk_gt_u32 s2, 0x1ff
	s_cbranch_scc1 .LBB0_714
	v_lshlrev_b32_e32 v0, 2, v129
	v_bfe_u32 v5, v129, 4, 2
	v_and_b32_e32 v64, 0xf00, v0
	v_mov_b32_e32 v65, 0
	v_lshl_add_u64 v[0:1], s[44:45], 0, v[64:65]
	v_lshlrev_b32_e32 v2, 4, v5
	v_mov_b32_e32 v3, v65
	v_lshl_add_u64 v[66:67], v[0:1], 0, v[2:3]
	v_lshl_add_u64 v[0:1], s[64:65], 0, v[64:65]
	v_lshrrev_b32_e32 v4, 4, v129
	v_lshl_add_u64 v[68:69], v[0:1], 0, v[2:3]
	v_and_b32_e32 v0, 7, v129
	v_lshlrev_b32_e32 v1, 8, v129
	v_and_b32_e32 v1, 0x3cf00, v1
	v_bitop3_b32 v2, v4, v0, 3 bitop3:0x6c
	v_bitop3_b32 v3, v5, v0, 4 bitop3:0x36
	v_bitop3_b32 v6, v5, v0, 8 bitop3:0x36
	v_bitop3_b32 v0, v5, v0, 12 bitop3:0x36
	v_add_u32_e32 v1, 0, v1
	v_lshlrev_b32_e32 v2, 4, v2
	v_lshlrev_b32_e32 v3, 4, v3
	v_lshlrev_b32_e32 v6, 4, v6
	v_lshlrev_b32_e32 v0, 4, v0
	v_lshlrev_b32_e32 v74, 2, v128
	v_lshlrev_b32_e32 v5, 12, v4
	s_brev_b32 s4, 32
	v_add_u32_e32 v75, 0xfffffe00, v129
	v_or3_b32 v76, v5, v74, s4
	s_lshl_b32 s12, s2, 6
	s_lshl_b32 s13, s3, 6
	s_lshl_b32 s14, s2, 3
	s_lshl_b32 s15, s3, 3
	v_lshl_add_u32 v77, v4, 8, 0
	v_lshlrev_b32_e32 v78, 2, v4
	v_bfrev_b32_e32 v79, 64
	s_mov_b32 s16, 0x8000
	s_mov_b32 s17, 0x10000
	s_mov_b32 s18, 0x18000
	v_add_u32_e32 v80, v1, v2
	v_add_u32_e32 v81, v1, v3
	v_add_u32_e32 v82, v1, v6
	v_add_u32_e32 v83, v1, v0
	s_mov_b64 s[4:5], 0x40000
	s_mov_b32 s19, s2

.LBB0_781:
	s_cmpk_gt_u32 s2, 0xff
	s_cbranch_scc1 .LBB0_788
	v_lshrrev_b32_e32 v44, 3, v129
	v_lshrrev_b32_e32 v0, 4, v129
	v_bfe_u32 v1, v129, 4, 2
	v_and_b32_e32 v2, 7, v129
	v_lshlrev_b32_e32 v3, 7, v129
	v_xor_b32_e32 v4, v44, v129
	v_and_b32_e32 v3, 0x1e780, v3
	v_bitop3_b32 v0, v0, v2, 3 bitop3:0x6c
	v_bitop3_b32 v2, v1, v2, 4 bitop3:0x36
	v_lshlrev_b32_e32 v4, 4, v4
	s_movk_i32 s4, 0x200
	v_add_u32_e32 v3, 0, v3
	v_lshlrev_b32_e32 v0, 4, v0
	v_lshlrev_b32_e32 v2, 4, v2
	v_lshlrev_b32_e32 v5, 7, v44
	v_and_b32_e32 v4, 0x70, v4
	v_mov_b32_e32 v35, 0
	v_and_b32_e32 v34, 0x3c00, v147
	v_cmp_gt_u32_e32 vcc, s4, v129
	v_add3_u32 v45, 0, v5, v4
	v_and_b32_e32 v46, 28, v148
	v_lshlrev_b32_e32 v32, 4, v1
	v_mov_b32_e32 v33, v35
	v_lshl_add_u64 v[36:37], s[46:47], 0, v[34:35]
	v_or_b32_e32 v47, 0x4000, v128
	s_lshl_b32 s10, s2, 6
	s_waitcnt lgkmcnt(0)
	s_lshl_b32 s11, s3, 6
	v_lshl_add_u64 v[38:39], s[66:67], 0, v[34:35]
	v_lshlrev_b32_e32 v48, 12, v128
	s_lshl_b32 s12, s2, 2
	s_lshl_b32 s13, s3, 2
	s_mov_b32 s14, 0x20000
	s_mov_b32 s15, 0x40000
	s_mov_b32 s16, 0x60000
	s_mov_b64 s[8:9], 0x100
	v_add_u32_e32 v49, v3, v0
	v_add_u32_e32 v50, v3, v2
	v_bfrev_b32_e32 v51, 64
	s_mov_b32 s17, s2
	s_branch .LBB0_784

.LBB0_917:
	s_cmpk_gt_u32 s2, 0xff
	s_cbranch_scc1 .LBB0_922
	v_bfe_u32 v9, v129, 4, 2
	v_and_b32_e32 v0, 0xf00, v148
	v_mov_b32_e32 v1, 0
	v_lshl_add_u64 v[2:3], s[44:45], 0, v[0:1]
	v_lshlrev_b32_e32 v4, 4, v9
	v_mov_b32_e32 v5, v1
	v_lshl_add_u64 v[6:7], s[36:37], 0, v[0:1]
	v_lshl_add_u64 v[2:3], v[2:3], 0, v[4:5]
	v_lshl_add_u64 v[4:5], v[6:7], 0, v[4:5]
	v_lshlrev_b32_e32 v6, 7, v129
	v_lshrrev_b32_e32 v8, 4, v129
	v_and_b32_e32 v0, 7, v129
	v_and_b32_e32 v6, 0x1e780, v6
	v_add_u32_e32 v11, 0, v6
	v_bitop3_b32 v6, v8, v0, 3 bitop3:0x6c
	v_bitop3_b32 v0, v9, v0, 4 bitop3:0x36
	v_lshrrev_b32_e32 v8, 3, v129
	v_lshlrev_b32_e32 v12, 4, v0
	v_xor_b32_e32 v0, v8, v129
	v_lshlrev_b32_e32 v0, 4, v0
	v_lshlrev_b32_e32 v10, 4, v6
	v_lshlrev_b32_e32 v6, 7, v8
	v_and_b32_e32 v0, 0x70, v0
	v_add3_u32 v9, 0, v6, v0
	v_and_b32_e32 v0, 28, v148
	s_movk_i32 s4, 0x200
	v_lshlrev_b32_e32 v0, 1, v0
	v_cmp_gt_u32_e64 s[4:5], s4, v129
	v_lshl_add_u64 v[6:7], s[46:47], 0, v[0:1]
	s_lshl_b32 s10, s2, 2
	s_waitcnt lgkmcnt(0)
	s_lshl_b32 s11, s3, 2
	s_lshl_b32 s12, s2, 6
	s_lshl_b32 s13, s3, 6
	v_add_u32_e32 v10, v11, v10
	v_add_u32_e32 v11, v11, v12
	s_mov_b32 s14, s2
	s_branch .LBB0_920

.LBB0_1010:
	s_or_b64 exec, exec, s[14:15]
	v_mfma_f32_16x16x32_bf16 v[212:215], v[80:83], v[4:7], 0
	v_mfma_f32_16x16x32_bf16 v[216:219], v[80:83], v[8:11], 0
	v_mfma_f32_16x16x32_bf16 v[220:223], v[80:83], v[12:15], 0
	v_mfma_f32_16x16x32_bf16 v[224:227], v[80:83], v[16:19], 0
	v_mfma_f32_16x16x32_bf16 v[232:235], v[80:83], v[20:23], 0
	v_mfma_f32_16x16x32_bf16 v[236:239], v[80:83], v[24:27], 0
	v_mfma_f32_16x16x32_bf16 v[240:243], v[80:83], v[28:31], 0
	v_mfma_f32_16x16x32_bf16 v[244:247], v[80:83], v[32:35], 0
	s_nop 1
	ds_write2_b32 v157, v212, v213 offset0:0 offset1:132
	ds_write2_b32 v250, v214, v215 offset0:8 offset1:140
	ds_write2_b32 v157, v216, v217 offset0:16 offset1:148
	ds_write2_b32 v250, v218, v219 offset0:24 offset1:156
	ds_write2_b32 v157, v220, v221 offset0:32 offset1:164
	ds_write2_b32 v250, v222, v223 offset0:40 offset1:172
	ds_write2_b32 v157, v224, v225 offset0:48 offset1:180
	ds_write2_b32 v250, v226, v227 offset0:56 offset1:188
	ds_write2_b32 v157, v232, v233 offset0:64 offset1:196
	ds_write2_b32 v250, v234, v235 offset0:72 offset1:204
	ds_write2_b32 v157, v236, v237 offset0:80 offset1:212
	ds_write2_b32 v250, v238, v239 offset0:88 offset1:220
	ds_write2_b32 v157, v240, v241 offset0:96 offset1:228
	ds_write2_b32 v250, v242, v243 offset0:104 offset1:236
	ds_write2_b32 v157, v244, v245 offset0:112 offset1:244
	ds_write2_b32 v250, v246, v247 offset0:120 offset1:252
	s_and_saveexec_b64 s[14:15], s[4:5]
	ds_write_b128 v160, v[80:83] offset:12800
	s_or_b64 exec, exec, s[14:15]
	s_cmp_eq_u32 s16, 0
	s_cbranch_scc1 .Ls5_first
	ds_read_b128 v[188:191], v161 offset:8448
	ds_read_b128 v[192:195], v161 offset:8512
	ds_read_b128 v[196:199], v161 offset:8576
	ds_read_b128 v[208:211], v161 offset:8640
	ds_read2_b64 v[80:83], v173 offset1:66
	ds_read2_b64 v[90:93], v173 offset0:132 offset1:198
	ds_read2_b64 v[100:103], v96 offset0:8 offset1:74
	ds_read2_b64 v[104:107], v96 offset0:140 offset1:206
	ds_read2_b64 v[108:111], v97 offset0:16 offset1:82
	ds_read2_b64 v[112:115], v97 offset0:148 offset1:214
	ds_read2_b64 v[174:177], v98 offset0:24 offset1:90
	ds_read2_b64 v[178:181], v98 offset0:156 offset1:222
	s_waitcnt lgkmcnt(11)
	v_mfma_f32_16x16x32_bf16 v[188:191], v[188:191], v[60:63], 0
	s_waitcnt lgkmcnt(10)
	v_mfma_f32_16x16x32_bf16 v[188:191], v[192:195], v[52:55], v[188:191]
	s_waitcnt lgkmcnt(9)
	v_mfma_f32_16x16x32_bf16 v[188:191], v[196:199], v[44:47], v[188:191]
	s_waitcnt lgkmcnt(8)
	v_mfma_f32_16x16x32_bf16 v[188:191], v[208:211], v[36:39], v[188:191]
	v_lshlrev_b32_e32 v200, 16, v200
	v_lshlrev_b32_e32 v202, 16, v202
	s_nop 7
	v_fma_f32 v200, v135, v200, v188
	v_mul_f32_e32 v203, 0x3d372713, v200
	v_mul_f32_e32 v203, v200, v203
	v_fma_f32 v203, v200, v203, v200
	v_mul_f32_e32 v203, 0xbfcc422a, v203
	v_mul_f32_e32 v203, 0x3fb8aa3b, v203
	v_exp_f32_e32 v203, v203
	s_nop 0
	v_add_f32_e32 v203, 1.0, v203
	v_div_scale_f32 v205, s[14:15], v203, v203, v200
	v_rcp_f32_e32 v188, v205
	s_nop 0
	v_fma_f32 v206, -v205, v188, 1.0
	v_fmac_f32_e32 v188, v206, v188
	v_div_scale_f32 v206, vcc, v200, v203, v200
	v_mul_f32_e32 v207, v206, v188
	v_fma_f32 v192, -v205, v207, v206
	v_fmac_f32_e32 v207, v192, v188
	v_fma_f32 v205, -v205, v207, v206
	v_div_fmas_f32 v205, v205, v188, v207
	v_div_fixup_f32 v200, v205, v203, v200
	v_fma_f32 v205, v135, v202, v189
	v_mul_f32_e32 v202, 0x3d372713, v205
	v_mul_f32_e32 v202, v205, v202
	v_fma_f32 v202, v205, v202, v205
	v_mul_f32_e32 v202, 0xbfcc422a, v202
	v_mul_f32_e32 v202, 0x3fb8aa3b, v202
	v_exp_f32_e32 v188, v202
	v_add_u32_e32 v189, s17, v64
	v_add_u32_e32 v202, 0, v189
	v_ashrrev_i32_e32 v203, 31, v202
	v_add_f32_e32 v188, 1.0, v188
	v_div_scale_f32 v206, s[14:15], v188, v188, v205
	v_rcp_f32_e32 v207, v206
	v_lshlrev_b64 v[202:203], 11, v[202:203]
	v_cvt_pk_bf16_f32 v200, v200, s0
	v_lshl_add_u64 v[202:203], v[48:49], 0, v[202:203]
	global_store_short v[202:203], v200, off
	v_fma_f32 v200, -v206, v207, 1.0
	v_fmac_f32_e32 v207, v200, v207
	v_div_scale_f32 v200, vcc, v205, v188, v205
	v_mul_f32_e32 v202, v200, v207
	v_fma_f32 v203, -v206, v202, v200
	v_fmac_f32_e32 v202, v203, v207
	v_fma_f32 v200, -v206, v202, v200
	v_div_fmas_f32 v200, v200, v207, v202
	v_lshlrev_b32_e32 v202, 16, v201
	v_fma_f32 v201, v135, v202, v190
	v_mul_f32_e32 v202, 0x3d372713, v201
	v_mul_f32_e32 v202, v201, v202
	v_fma_f32 v202, v201, v202, v201
	v_mul_f32_e32 v202, 0xbfcc422a, v202
	v_mul_f32_e32 v202, 0x3fb8aa3b, v202
	v_div_fixup_f32 v200, v200, v188, v205
	v_exp_f32_e32 v205, v202
	v_add_u32_e32 v202, 1, v189
	v_ashrrev_i32_e32 v203, 31, v202
	v_lshlrev_b64 v[202:203], 11, v[202:203]
	v_add_f32_e32 v205, 1.0, v205
	v_div_scale_f32 v188, s[14:15], v205, v205, v201
	v_rcp_f32_e32 v190, v188
	v_cvt_pk_bf16_f32 v200, v200, s0
	v_lshl_add_u64 v[202:203], v[48:49], 0, v[202:203]
	global_store_short v[202:203], v200, off
	v_fma_f32 v200, -v188, v190, 1.0
	v_fmac_f32_e32 v190, v200, v190
	v_div_scale_f32 v200, vcc, v201, v205, v201
	v_mul_f32_e32 v202, v200, v190
	v_fma_f32 v203, -v188, v202, v200
	v_fmac_f32_e32 v202, v203, v190
	v_fma_f32 v200, -v188, v202, v200
	v_div_fmas_f32 v200, v200, v190, v202
	v_lshlrev_b32_e32 v202, 16, v204
	v_fmac_f32_e32 v191, v135, v202
	v_mul_f32_e32 v202, 0x3d372713, v191
	v_mul_f32_e32 v202, v191, v202
	v_fma_f32 v202, v191, v202, v191
	v_mul_f32_e32 v202, 0xbfcc422a, v202
	v_mul_f32_e32 v202, 0x3fb8aa3b, v202
	v_div_fixup_f32 v200, v200, v205, v201
	v_exp_f32_e32 v201, v202
	v_add_u32_e32 v202, 2, v189
	v_ashrrev_i32_e32 v203, 31, v202
	v_lshlrev_b64 v[202:203], 11, v[202:203]
	v_add_f32_e32 v201, 1.0, v201
	v_div_scale_f32 v204, s[14:15], v201, v201, v191
	v_rcp_f32_e32 v205, v204
	v_cvt_pk_bf16_f32 v200, v200, s0
	v_lshl_add_u64 v[202:203], v[48:49], 0, v[202:203]
	global_store_short v[202:203], v200, off
	v_fma_f32 v200, -v204, v205, 1.0
	v_fmac_f32_e32 v205, v200, v205
	v_div_scale_f32 v200, vcc, v191, v201, v191
	v_mul_f32_e32 v202, v200, v205
	v_fma_f32 v203, -v204, v202, v200
	v_fmac_f32_e32 v202, v203, v205
	v_fma_f32 v200, -v204, v202, v200
	v_div_fmas_f32 v200, v200, v205, v202
	v_add_u32_e32 v202, 3, v189
	v_ashrrev_i32_e32 v203, 31, v202
	v_div_fixup_f32 v200, v200, v201, v191
	v_lshlrev_b64 v[202:203], 11, v[202:203]
	v_cvt_pk_bf16_f32 v200, v200, s0
	v_lshl_add_u64 v[202:203], v[48:49], 0, v[202:203]
	global_store_short v[202:203], v200, off
	s_branch .Ls5_scan

.Ls5_scan:
	s_cmpk_lt_u32 s16, 0x1f0
	v_lshl_add_u64 v[88:89], v[88:89], 0, s[12:13]
	s_waitcnt lgkmcnt(7)
	v_fma_f32 v66, v138, v84, v80
	v_fma_f32 v67, v138, v85, v81
	v_fma_f32 v2, -v140, v85, v66
	v_fma_f32 v3, v140, v84, v67
	v_cvt_pk_bf16_f32 v1, v2, v3
	v_add_u32_e32 v251, 8448, v165
	v_fma_f32 v66, v138, v2, v82
	v_fma_f32 v67, v138, v3, v83
	v_fma_f32 v84, -v140, v3, v66
	v_fma_f32 v85, v140, v2, v67
	v_cvt_pk_bf16_f32 v65, v84, v85
	ds_write2_b32 v251, v1, v65 offset1:68
	s_waitcnt lgkmcnt(7)
	v_fma_f32 v66, v138, v84, v90
	v_fma_f32 v67, v138, v85, v91
	v_fma_f32 v2, -v140, v85, v66
	v_fma_f32 v3, v140, v84, v67
	v_cvt_pk_bf16_f32 v1, v2, v3
	v_add_u32_e32 v251, 8992, v165
	v_fma_f32 v66, v138, v2, v92
	v_fma_f32 v67, v138, v3, v93
	v_fma_f32 v84, -v140, v3, v66
	v_fma_f32 v85, v140, v2, v67
	v_cvt_pk_bf16_f32 v65, v84, v85
	ds_write2_b32 v251, v1, v65 offset1:68
	s_waitcnt lgkmcnt(7)
	v_fma_f32 v66, v138, v84, v100
	v_fma_f32 v67, v138, v85, v101
	v_fma_f32 v2, -v140, v85, v66
	v_fma_f32 v3, v140, v84, v67
	v_cvt_pk_bf16_f32 v1, v2, v3
	v_add_u32_e32 v251, 9536, v165
	v_fma_f32 v66, v138, v2, v102
	v_fma_f32 v67, v138, v3, v103
	v_fma_f32 v84, -v140, v3, v66
	v_fma_f32 v85, v140, v2, v67
	v_cvt_pk_bf16_f32 v65, v84, v85
	ds_write2_b32 v251, v1, v65 offset1:68
	s_waitcnt lgkmcnt(7)
	v_fma_f32 v66, v138, v84, v104
	v_fma_f32 v67, v138, v85, v105
	v_fma_f32 v2, -v140, v85, v66
	v_fma_f32 v3, v140, v84, v67
	v_cvt_pk_bf16_f32 v1, v2, v3
	v_add_u32_e32 v251, 10080, v165
	v_fma_f32 v66, v138, v2, v106
	v_fma_f32 v67, v138, v3, v107
	v_fma_f32 v84, -v140, v3, v66
	v_fma_f32 v85, v140, v2, v67
	v_cvt_pk_bf16_f32 v65, v84, v85
	ds_write2_b32 v251, v1, v65 offset1:68
	s_waitcnt lgkmcnt(7)
	v_fma_f32 v66, v138, v84, v108
	v_fma_f32 v67, v138, v85, v109
	v_fma_f32 v2, -v140, v85, v66
	v_fma_f32 v3, v140, v84, v67
	v_cvt_pk_bf16_f32 v1, v2, v3
	v_add_u32_e32 v251, 10624, v165
	v_fma_f32 v66, v138, v2, v110
	v_fma_f32 v67, v138, v3, v111
	v_fma_f32 v84, -v140, v3, v66
	v_fma_f32 v85, v140, v2, v67
	v_cvt_pk_bf16_f32 v65, v84, v85
	ds_write2_b32 v251, v1, v65 offset1:68
	s_waitcnt lgkmcnt(7)
	v_fma_f32 v66, v138, v84, v112
	v_fma_f32 v67, v138, v85, v113
	v_fma_f32 v2, -v140, v85, v66
	v_fma_f32 v3, v140, v84, v67
	v_cvt_pk_bf16_f32 v1, v2, v3
	v_add_u32_e32 v251, 11168, v165
	v_fma_f32 v66, v138, v2, v114
	v_fma_f32 v67, v138, v3, v115
	v_fma_f32 v84, -v140, v3, v66
	v_fma_f32 v85, v140, v2, v67
	v_cvt_pk_bf16_f32 v65, v84, v85
	ds_write2_b32 v251, v1, v65 offset1:68
	s_waitcnt lgkmcnt(7)
	v_fma_f32 v66, v138, v84, v174
	v_fma_f32 v67, v138, v85, v175
	v_fma_f32 v2, -v140, v85, v66
	v_fma_f32 v3, v140, v84, v67
	v_cvt_pk_bf16_f32 v1, v2, v3
	v_add_u32_e32 v251, 11712, v165
	v_fma_f32 v66, v138, v2, v176
	v_fma_f32 v67, v138, v3, v177
	v_fma_f32 v84, -v140, v3, v66
	v_fma_f32 v85, v140, v2, v67
	v_cvt_pk_bf16_f32 v65, v84, v85
	ds_write2_b32 v251, v1, v65 offset1:68
	s_waitcnt lgkmcnt(7)
	v_fma_f32 v66, v138, v84, v178
	v_fma_f32 v67, v138, v85, v179
	v_fma_f32 v2, -v140, v85, v66
	v_fma_f32 v3, v140, v84, v67
	v_cvt_pk_bf16_f32 v1, v2, v3
	v_add_u32_e32 v251, 12256, v165
	v_fma_f32 v66, v138, v2, v180
	v_fma_f32 v67, v138, v3, v181
	v_fma_f32 v84, -v140, v3, v66
	v_fma_f32 v85, v140, v2, v67
	v_cvt_pk_bf16_f32 v65, v84, v85
	ds_write2_b32 v251, v1, v65 offset1:68
	ds_read_u16 v200, v166 offset:12800
	ds_read_u16 v202, v167 offset:12800
	ds_read_u16 v201, v168 offset:12800
	ds_read_u16 v204, v169 offset:12800
	s_waitcnt lgkmcnt(0)
	s_cbranch_scc0 .Ls5_lastE
	s_waitcnt vmcnt(4)
	v_mov_b64_e32 v[82:83], v[70:71]
	v_mov_b64_e32 v[80:81], v[68:69]
	v_mov_b64_e32 v[68:69], v[72:73]
	v_mov_b64_e32 v[70:71], v[74:75]
	v_mov_b64_e32 v[72:73], v[76:77]
	v_mov_b64_e32 v[74:75], v[78:79]
	v_mov_b64_e32 v[78:79], v[42:43]
	s_mov_b32 s17, s16
	v_mov_b64_e32 v[76:77], v[40:41]
	s_branch .LBB0_1008

.LBB0_1121:
	s_cmpk_gt_u32 s2, 0xff
	s_cbranch_scc1 .LBB0_1128
	v_bfe_u32 v7, v129, 2, 1
	v_and_b32_e32 v64, 0xf00, v143
	v_mov_b32_e32 v65, 0
	v_lshlrev_b32_e32 v8, 3, v7
	v_bfe_u32 v9, v143, 2, 2
	v_lshl_add_u64 v[0:1], s[44:45], 0, v[64:65]
	v_lshlrev_b32_e32 v2, 4, v144
	v_mov_b32_e32 v3, v65
	v_or_b32_e32 v10, v8, v9
	v_bfe_u32 v11, v129, 3, 3
	v_lshl_add_u64 v[66:67], v[0:1], 0, v[2:3]
	v_lshl_add_u64 v[0:1], s[38:39], 0, v[64:65]
	v_bitop3_b32 v8, v8, v11, v9 bitop3:0x36
	v_bitop3_b32 v9, v10, v11, 4 bitop3:0x36
	v_lshlrev_b32_e32 v10, 8, v142
	v_lshl_add_u64 v[68:69], v[0:1], 0, v[2:3]
	v_and_b32_e32 v0, 7, v129
	v_lshlrev_b32_e32 v1, 8, v129
	v_lshl_add_u32 v8, v8, 4, 0
	v_lshl_add_u32 v9, v9, 4, 0
	v_or_b32_e32 v11, 0x10000, v10
	v_and_b32_e32 v1, 0x3cf00, v1
	v_bitop3_b32 v2, v144, v129, 7 bitop3:0x78
	v_bitop3_b32 v3, v144, v0, 4 bitop3:0x36
	v_bitop3_b32 v5, v144, v0, 8 bitop3:0x36
	v_bitop3_b32 v0, v144, v0, 12 bitop3:0x36
	v_add_u32_e32 v78, v8, v11
	v_add_u32_e32 v79, v9, v11
	v_or_b32_e32 v11, 0x14000, v10
	v_lshlrev_b32_e32 v4, 10, v128
	s_movk_i32 s4, 0x200
	v_add_u32_e32 v1, 0, v1
	v_lshlrev_b32_e32 v2, 4, v2
	v_lshlrev_b32_e32 v3, 4, v3
	v_lshlrev_b32_e32 v5, 4, v5
	v_lshlrev_b32_e32 v6, 4, v0
	v_and_b32_e32 v0, 12, v143
	v_add_u32_e32 v76, v8, v10
	v_add_u32_e32 v77, v9, v10
	v_add_u32_e32 v80, v8, v11
	v_add_u32_e32 v81, v9, v11
	v_or_b32_e32 v11, 0x18000, v10
	v_or_b32_e32 v10, 0x1c000, v10
	v_lshlrev_b32_e32 v7, 4, v7
	v_cmp_gt_u32_e64 s[4:5], s4, v129
	s_mov_b32 s10, 0x10000
	s_mov_b32 s11, 0x18000
	v_add_u32_e32 v82, v8, v11
	v_add_u32_e32 v83, v9, v11
	v_add_u32_e32 v84, v8, v10
	v_add_u32_e32 v85, v9, v10
	v_lshlrev_b32_e32 v86, 1, v4
	s_mov_b32 s12, 0x8000
	v_add_u32_e32 v87, v1, v2
	v_add_u32_e32 v88, v1, v3
	v_add_u32_e32 v89, v1, v5
	v_add_u32_e32 v90, v1, v6
	v_lshlrev_b32_e32 v91, 1, v7
	v_lshlrev_b32_e32 v70, 1, v0
	s_mov_b32 s13, s2
	s_branch .LBB0_1124

.LBB0_1315:
	s_cmpk_gt_u32 s2, 0x1ff
	s_cbranch_scc1 .LBB0_1322
	v_lshlrev_b32_e32 v0, 2, v129
	v_bfe_u32 v5, v129, 4, 2
	v_and_b32_e32 v64, 0xf00, v0
	v_mov_b32_e32 v65, 0
	v_lshl_add_u64 v[0:1], s[44:45], 0, v[64:65]
	v_lshlrev_b32_e32 v2, 4, v5
	v_mov_b32_e32 v3, v65
	v_lshl_add_u64 v[66:67], v[0:1], 0, v[2:3]
	v_lshl_add_u64 v[0:1], s[8:9], 0, v[64:65]
	v_lshrrev_b32_e32 v4, 4, v129
	v_lshl_add_u64 v[68:69], v[0:1], 0, v[2:3]
	v_and_b32_e32 v0, 7, v129
	v_lshlrev_b32_e32 v1, 8, v129
	v_and_b32_e32 v1, 0x3cf00, v1
	v_bitop3_b32 v2, v4, v0, 3 bitop3:0x6c
	v_bitop3_b32 v3, v5, v0, 4 bitop3:0x36
	v_bitop3_b32 v6, v5, v0, 8 bitop3:0x36
	v_bitop3_b32 v0, v5, v0, 12 bitop3:0x36
	v_add_u32_e32 v1, 0, v1
	v_lshlrev_b32_e32 v2, 4, v2
	v_lshlrev_b32_e32 v3, 4, v3
	v_lshlrev_b32_e32 v6, 4, v6
	v_lshlrev_b32_e32 v0, 4, v0
	v_lshlrev_b32_e32 v74, 2, v128
	v_lshlrev_b32_e32 v5, 12, v4
	s_brev_b32 s4, 32
	v_add_u32_e32 v75, 0xfffffe00, v129
	v_or3_b32 v76, v5, v74, s4
	s_lshl_b32 s12, s2, 6
	s_waitcnt lgkmcnt(0)
	s_lshl_b32 s13, s3, 6
	s_lshl_b32 s14, s2, 3
	s_lshl_b32 s15, s3, 3
	v_lshl_add_u32 v77, v4, 8, 0
	v_lshlrev_b32_e32 v78, 2, v4
	v_bfrev_b32_e32 v79, 64
	s_mov_b32 s16, 0x8000
	s_mov_b32 s17, 0x10000
	s_mov_b32 s18, 0x18000
	v_add_u32_e32 v80, v1, v2
	v_add_u32_e32 v81, v1, v3
	v_add_u32_e32 v82, v1, v6
	v_add_u32_e32 v83, v1, v0
	s_mov_b64 s[4:5], 0x40000
	s_mov_b32 s19, s2

.LBB0_1389:
	s_cmpk_gt_u32 s2, 0xff
	s_cbranch_scc1 .LBB0_1396
	v_lshrrev_b32_e32 v0, 4, v129
	v_bfe_u32 v1, v129, 4, 2
	v_and_b32_e32 v2, 7, v129
	v_lshlrev_b32_e32 v3, 7, v129
	v_xor_b32_e32 v4, v148, v129
	v_and_b32_e32 v3, 0x1e780, v3
	v_bitop3_b32 v0, v0, v2, 3 bitop3:0x6c
	v_bitop3_b32 v2, v1, v2, 4 bitop3:0x36
	v_lshlrev_b32_e32 v4, 4, v4
	s_movk_i32 s4, 0x200
	v_add_u32_e32 v3, 0, v3
	v_lshlrev_b32_e32 v0, 4, v0
	v_lshlrev_b32_e32 v2, 4, v2
	v_lshlrev_b32_e32 v5, 7, v148
	v_and_b32_e32 v4, 0x70, v4
	v_mov_b32_e32 v35, 0
	v_and_b32_e32 v34, 0x3c00, v147
	v_cmp_gt_u32_e32 vcc, s4, v129
	v_add3_u32 v44, 0, v5, v4
	v_and_b32_e32 v45, 28, v149
	v_lshlrev_b32_e32 v32, 4, v1
	v_mov_b32_e32 v33, v35
	v_lshl_add_u64 v[36:37], s[46:47], 0, v[34:35]
	v_or_b32_e32 v46, 0x4000, v128
	s_lshl_b32 s10, s2, 6
	s_waitcnt lgkmcnt(0)
	s_lshl_b32 s11, s3, 6
	v_lshl_add_u64 v[38:39], s[66:67], 0, v[34:35]
	v_lshlrev_b32_e32 v47, 12, v128
	s_lshl_b32 s12, s2, 2
	s_lshl_b32 s13, s3, 2
	s_mov_b32 s14, 0x20000
	s_mov_b32 s15, 0x40000
	s_mov_b32 s16, 0x60000
	s_mov_b32 s17, 0x800000
	s_mov_b32 s18, 0x820000
	s_mov_b64 s[8:9], 0x100
	v_add_u32_e32 v48, v3, v0
	v_add_u32_e32 v49, v3, v2
	v_bfrev_b32_e32 v50, 64
	s_mov_b32 s19, s2
	s_branch .LBB0_1392
